# rstd phases: own-panel rows + block barrier instead of grid barrier (grid 256)
# baseline (speedup 1.0000x reference)
.LBB0_45:
	s_add_i32 s0, s58, -1
	s_mul_hi_i32 s1, s0, 0x66666667
	s_lshr_b32 s2, s1, 31
	s_ashr_i32 s22, s1, 2
	s_add_i32 s22, s22, s2
	s_mul_i32 s1, s22, 10
	s_sub_i32 s70, s0, s1
	s_mov_b64 s[24:25], -1
	s_mov_b64 s[2:3], 0
	s_cmp_lt_i32 s70, 7
	s_mov_b64 s[0:1], 0
	s_cbranch_scc1 .LBB0_64
	s_cmp_eq_u32 s70, 7
	s_mov_b64 s[0:1], -1
	s_cbranch_scc0 .LBB0_51
	s_waitcnt vmcnt(0)
	v_mov_b32_e32 v0, v165
	v_readlane_b32 s1, v253, 3
	s_cmpk_lg_i32 s1, 0x100
	s_cbranch_scc1 .Lrs_orig0
	s_and_b32 s0, s10, 7
	s_lshr_b32 s1, s10, 3
	s_and_b32 s1, s1, 7
	s_lshl_b32 s0, s0, 3
	s_add_i32 s1, s0, s1
	v_and_b32_e32 v0, 0xff, v0
	v_lshl_add_u32 v0, s1, 8, v0
	s_branch .Lrs_map0
.Lrs_orig0:
	v_lshl_add_u32 v0, s10, 9, v0
.Lrs_map0:
	s_movk_i32 s0, 0x4000
	v_cmp_gt_i32_e32 vcc, s0, v0
	s_and_saveexec_b64 s[24:25], vcc
	v_readlane_b32 s8, v253, 4
	s_mov_b64 s[4:5], 0x38100000
	s_mov_b64 s[6:7], 0x38100040
	v_readlane_b32 s9, v253, 5
	s_cbranch_execz .LBB0_50
	v_readlane_b32 s0, v253, 3
	s_lshl_b32 s28, s0, 9
	v_ashrrev_i32_e32 v1, 31, v0
	v_readlane_b32 s0, v251, 49
	v_readlane_b32 s1, v251, 50
	s_ashr_i32 s29, s28, 31
	v_lshlrev_b64 v[4:5], 7, v[0:1]
	v_lshl_add_u64 v[2:3], v[0:1], 2, s[0:1]
	s_lshl_b64 s[30:31], s[28:29], 2
	v_lshl_add_u64 v[4:5], s[90:91], 0, v[4:5]
	s_lshl_b64 s[34:35], s[28:29], 7
	s_mov_b64 s[36:37], 0

.LBB0_67:
	s_waitcnt vmcnt(0)
	v_mov_b32_e32 v0, v165
	v_readlane_b32 s1, v253, 3
	s_cmpk_lg_i32 s1, 0x100
	s_cbranch_scc1 .Lrs_orig1
	s_and_b32 s0, s10, 7
	s_lshr_b32 s1, s10, 3
	s_and_b32 s1, s1, 7
	s_lshl_b32 s0, s0, 3
	s_add_i32 s1, s0, s1
	v_and_b32_e32 v0, 0xff, v0
	v_lshl_add_u32 v0, s1, 8, v0
	s_branch .Lrs_map1

.Lrs_map1:
	s_movk_i32 s0, 0x4000
	v_cmp_gt_i32_e32 vcc, s0, v0
	s_and_saveexec_b64 s[2:3], vcc
	v_readlane_b32 s8, v253, 4
	s_mov_b64 s[4:5], 0x38100000
	s_mov_b64 s[6:7], 0x38100040
	v_readlane_b32 s9, v253, 5
	s_cbranch_execz .LBB0_70
	v_readlane_b32 s0, v253, 3
	s_lshl_b32 s24, s0, 9
	s_waitcnt lgkmcnt(0)
	v_ashrrev_i32_e32 v1, 31, v0
	v_readlane_b32 s0, v251, 49
	v_readlane_b32 s1, v251, 50
	s_ashr_i32 s25, s24, 31
	v_lshlrev_b64 v[4:5], 7, v[0:1]
	v_lshl_add_u64 v[2:3], v[0:1], 2, s[0:1]
	s_lshl_b64 s[28:29], s[24:25], 2
	v_lshl_add_u64 v[4:5], s[90:91], 0, v[4:5]
	s_lshl_b64 s[30:31], s[24:25], 7
	s_mov_b64 s[34:35], 0

.LBB0_2452:
	s_add_i32 s22, s58, 1
	v_readlane_b32 s0, v253, 3
	s_cmpk_lg_i32 s0, 0x100
	s_cbranch_scc1 .Lrs_norm
	s_mov_b32 vcc_lo, 0x90240900
	s_mov_b32 vcc_hi, 0x40
	s_lshr_b64 vcc, vcc, s58
	s_bitcmp1_b32 vcc_lo, 0
	s_cbranch_scc0 .Lrs_norm
	s_waitcnt vmcnt(0) lgkmcnt(0)
	s_barrier
	buffer_inv sc1
	s_waitcnt vmcnt(0)
	s_cmp_eq_u32 s22, s22
	s_branch .Lrs_join

.Lrs_join:
	s_cbranch_scc0 .LBB0_2453
	s_getpc_b64 s[98:99]
